# baseline (speedup 1.0000x reference)
.LBB0_486:
	v_add3_u32 v0, s78, v207, v235
	v_cvt_pk_bf16_f32 v44, v2, v3
	v_add_u32_e32 v2, 0x2000, v0
	ds_read2_b64 v[52:55], v2 offset0:128 offset1:132
	v_add_u32_e32 v3, 0x2800, v0
	ds_read2_b64 v[68:71], v3 offset0:160 offset1:164
	v_cvt_pk_bf16_f32 v45, v156, v157
	v_cvt_pk_bf16_f32 v46, v158, v159
	v_cvt_pk_bf16_f32 v47, v160, v161
	v_cvt_pk_bf16_f32 v48, v84, v85
	s_waitcnt lgkmcnt(0)
	v_mov_b32_e32 v72, v68
	v_mov_b32_e32 v73, v69
	s_setprio 3
	v_mfma_f32_16x16x32_bf16 v[56:59], v[52:55], v[44:47], v[104:107]
	v_cvt_pk_bf16_f32 v49, v86, v87
	v_cvt_pk_bf16_f32 v50, v88, v89
	v_cvt_pk_bf16_f32 v51, v90, v91
	v_add_u32_e32 v104, 0x3000, v0
	v_add_u32_e32 v0, 0x3800, v0
	ds_read2_b64 v[84:87], v0 offset0:232 offset1:236
	v_mfma_f32_16x16x32_bf16 v[52:55], v[52:55], v[48:51], v[80:83]
	v_cvt_pk_bf16_f32 v60, v162, v163
	v_cvt_pk_bf16_f32 v61, v164, v165
	v_cvt_pk_bf16_f32 v62, v166, v167
	v_mfma_f32_16x16x32_bf16 v[80:83], v[70:73], v[44:47], v[92:95]
	s_waitcnt lgkmcnt(0)
	v_mov_b32_e32 v88, v84
	v_mov_b32_e32 v89, v85
	v_cvt_pk_bf16_f32 v63, v168, v169
	v_mfma_f32_16x16x32_bf16 v[68:71], v[70:73], v[48:51], v[76:79]
	ds_read2_b64 v[72:75], v104 offset0:200 offset1:204
	v_cvt_pk_bf16_f32 v64, v116, v117
	v_cvt_pk_bf16_f32 v65, v118, v119
	s_waitcnt lgkmcnt(0)
	v_mfma_f32_16x16x32_bf16 v[76:79], v[72:75], v[44:47], v[100:103]
	v_cvt_pk_bf16_f32 v66, v120, v121
	v_cvt_pk_bf16_f32 v67, v122, v123
	v_mfma_f32_16x16x32_bf16 v[72:75], v[72:75], v[48:51], v[112:115]
	v_mfma_f32_16x16x32_bf16 v[92:95], v[86:89], v[48:51], v[108:111]
	ds_read2_b64 v[48:51], v2 offset0:136 offset1:140
	v_mfma_f32_16x16x32_bf16 v[44:47], v[86:89], v[44:47], v[96:99]
	s_waitcnt lgkmcnt(0)
	v_mfma_f32_16x16x32_bf16 v[88:91], v[48:51], v[60:63], v[56:59]
	v_mfma_f32_16x16x32_bf16 v[56:59], v[48:51], v[64:67], v[52:55]
	ds_read2_b64 v[48:51], v3 offset0:168 offset1:172
	s_waitcnt lgkmcnt(0)
	s_nop 0
	v_mov_b32_e32 v52, v48
	v_mov_b32_e32 v53, v49
	s_nop 1
	v_mfma_f32_16x16x32_bf16 v[84:87], v[50:53], v[60:63], v[80:83]
	v_mfma_f32_16x16x32_bf16 v[52:55], v[50:53], v[64:67], v[68:71]
	ds_read2_b64 v[48:51], v104 offset0:192 offset1:196
	s_nop 1
	ds_read2_b64 v[68:71], v0 offset0:224 offset1:228
	s_waitcnt lgkmcnt(1)
	v_mfma_f32_16x16x32_bf16 v[80:83], v[48:51], v[60:63], v[76:79]
	v_mfma_f32_16x16x32_bf16 v[48:51], v[48:51], v[64:67], v[72:75]
	s_waitcnt lgkmcnt(0)
	s_nop 1
	v_mov_b32_e32 v72, v68
	v_mov_b32_e32 v73, v69
	s_nop 1
	v_mfma_f32_16x16x32_bf16 v[76:79], v[70:73], v[60:63], v[44:47]
	v_mfma_f32_16x16x32_bf16 v[44:47], v[70:73], v[64:67], v[92:95]
	s_branch .LBB0_669

.LBB0_758:
	v_cndmask_b32_e64 v149, v193, -v148, s[10:11]
	v_fmamk_f32 v94, v94, 0x3e38aa3b, v149
	v_exp_f32_e32 v94, v94
	v_fmamk_f32 v95, v95, 0x3e38aa3b, v149
	v_exp_f32_e32 v95, v95
	v_fmamk_f32 v96, v96, 0x3e38aa3b, v149
	v_exp_f32_e32 v96, v96
	v_fmamk_f32 v97, v97, 0x3e38aa3b, v149
	v_exp_f32_e32 v97, v97
	v_fmamk_f32 v90, v90, 0x3e38aa3b, v149
	v_add_f32_e32 v150, 0, v94
	v_exp_f32_e32 v90, v90
	v_fmamk_f32 v91, v91, 0x3e38aa3b, v149
	v_add_f32_e32 v150, v95, v150
	v_exp_f32_e32 v91, v91
	v_fmamk_f32 v92, v92, 0x3e38aa3b, v149
	v_add_f32_e32 v150, v96, v150
	v_exp_f32_e32 v92, v92
	v_fmamk_f32 v93, v93, 0x3e38aa3b, v149
	v_add_f32_e32 v150, v97, v150
	v_exp_f32_e32 v93, v93
	v_fmamk_f32 v86, v86, 0x3e38aa3b, v149
	v_add_f32_e32 v150, v90, v150
	v_exp_f32_e32 v86, v86
	v_fmamk_f32 v87, v87, 0x3e38aa3b, v149
	v_add_f32_e32 v150, v91, v150
	v_exp_f32_e32 v87, v87
	v_fmamk_f32 v88, v88, 0x3e38aa3b, v149
	v_add_f32_e32 v150, v92, v150
	v_exp_f32_e32 v88, v88
	v_fmamk_f32 v89, v89, 0x3e38aa3b, v149
	v_add_f32_e32 v150, v93, v150
	v_exp_f32_e32 v89, v89
	v_fmamk_f32 v82, v82, 0x3e38aa3b, v149
	v_add_f32_e32 v150, v86, v150
	v_exp_f32_e32 v151, v82
	v_add_f32_e32 v150, v87, v150
	v_add_f32_e32 v150, v88, v150
	v_add_f32_e32 v150, v89, v150
	v_fmamk_f32 v83, v83, 0x3e38aa3b, v149
	v_add_f32_e32 v82, v151, v150
	v_exp_f32_e32 v150, v83
	v_fmamk_f32 v83, v84, 0x3e38aa3b, v149
	v_exp_f32_e32 v84, v83
	v_fmac_f32_e32 v149, 0x3e38aa3b, v85
	v_exp_f32_e32 v85, v149
	v_cndmask_b32_e64 v83, v193, -v147, s[96:97]
	v_add_f32_e32 v82, v150, v82
	v_fmamk_f32 v66, v66, 0x3e38aa3b, v83
	v_add_f32_e32 v82, v84, v82
	v_exp_f32_e32 v153, v66
	v_fmamk_f32 v66, v67, 0x3e38aa3b, v83
	v_add_f32_e32 v82, v85, v82
	v_fmamk_f32 v74, v74, 0x3e38aa3b, v83
	v_exp_f32_e32 v154, v66
	v_fmamk_f32 v66, v68, 0x3e38aa3b, v83
	v_fmac_f32_e32 v82, v126, v130
	v_exp_f32_e32 v126, v74
	v_fmamk_f32 v74, v75, 0x3e38aa3b, v83
	v_exp_f32_e32 v155, v66
	v_fmamk_f32 v66, v69, 0x3e38aa3b, v83
	v_exp_f32_e32 v130, v74
	v_fmamk_f32 v74, v76, 0x3e38aa3b, v83
	v_exp_f32_e32 v156, v66
	v_fmamk_f32 v66, v78, 0x3e38aa3b, v83
	v_exp_f32_e32 v149, v74
	v_fmamk_f32 v74, v77, 0x3e38aa3b, v83
	v_exp_f32_e32 v78, v66
	v_fmamk_f32 v66, v79, 0x3e38aa3b, v83
	v_exp_f32_e32 v152, v74
	v_fmamk_f32 v70, v70, 0x3e38aa3b, v83
	v_fmamk_f32 v71, v71, 0x3e38aa3b, v83
	v_fmamk_f32 v72, v72, 0x3e38aa3b, v83
	v_fmamk_f32 v73, v73, 0x3e38aa3b, v83
	v_exp_f32_e32 v79, v66
	v_fmamk_f32 v66, v80, 0x3e38aa3b, v83
	v_fmac_f32_e32 v83, 0x3e38aa3b, v81
	v_exp_f32_e32 v70, v70
	v_exp_f32_e32 v71, v71
	v_exp_f32_e32 v81, v83
	v_add_f32_e32 v83, 0, v126
	v_add_f32_e32 v83, v130, v83
	v_exp_f32_e32 v72, v72
	v_add_f32_e32 v83, v149, v83
	v_exp_f32_e32 v73, v73
	v_add_f32_e32 v83, v152, v83
	v_cvt_pk_bf16_f32 v76, v70, v71
	v_add_f32_e32 v70, v70, v83
	v_add_f32_e32 v70, v71, v70
	v_add_f32_e32 v70, v72, v70
	v_add_f32_e32 v70, v73, v70
	v_add_f32_e32 v70, v153, v70
	v_add_f32_e32 v70, v154, v70
	v_exp_f32_e32 v80, v66
	v_add_f32_e32 v70, v155, v70
	v_add_f32_e32 v70, v156, v70
	v_add_f32_e32 v70, v78, v70
	v_add_f32_e32 v70, v79, v70
	v_cvt_pk_bf16_f32 v69, v80, v81
	v_add_f32_e32 v70, v80, v70
	v_cvt_pk_bf16_f32 v80, v90, v91
	v_add3_u32 v90, s9, v133, v143
	v_add_u32_e32 v91, 0x2000, v90
	v_cvt_pk_bf16_f32 v77, v72, v73
	v_add_f32_e32 v83, v81, v70
	v_cvt_pk_bf16_f32 v70, v86, v87
	v_cvt_pk_bf16_f32 v73, v84, v85
	ds_read2_b64 v[84:87], v91 offset0:128 offset1:132
	v_cvt_pk_bf16_f32 v74, v126, v130
	v_cvt_pk_bf16_f32 v75, v149, v152
	v_cvt_pk_bf16_f32 v68, v78, v79
	v_cvt_pk_bf16_f32 v78, v94, v95
	v_cvt_pk_bf16_f32 v79, v96, v97
	v_cvt_pk_bf16_f32 v81, v92, v93
	v_add_u32_e32 v92, 0x2800, v90
	s_waitcnt lgkmcnt(0)
	s_setprio 3
	v_mfma_f32_16x16x32_bf16 v[62:65], v[84:87], v[74:77], v[62:65]
	v_cvt_pk_bf16_f32 v71, v88, v89
	v_add_u32_e32 v93, 0x3000, v90
	v_add_u32_e32 v90, 0x3800, v90
	v_mfma_f32_16x16x32_bf16 v[46:49], v[84:87], v[78:81], v[46:49]
	ds_read2_b64 v[84:87], v92 offset0:160 offset1:164
	v_cvt_pk_bf16_f32 v66, v153, v154
	v_cvt_pk_bf16_f32 v67, v155, v156
	v_cvt_pk_bf16_f32 v72, v151, v150
	v_fmac_f32_e32 v83, v127, v128
	s_waitcnt lgkmcnt(0)
	v_mov_b32_e32 v88, v84
	v_mov_b32_e32 v89, v85
	v_mov_b32_e32 v127, v83
	v_mov_b32_e32 v126, v82
	v_mfma_f32_16x16x32_bf16 v[50:53], v[86:89], v[74:77], v[50:53]
	v_mov_b32_e32 v130, v148
	v_mov_b32_e32 v128, v147
	v_mfma_f32_16x16x32_bf16 v[42:45], v[86:89], v[78:81], v[42:45]
	ds_read2_b64 v[84:87], v93 offset0:200 offset1:204
	s_waitcnt lgkmcnt(0)
	v_mfma_f32_16x16x32_bf16 v[58:61], v[84:87], v[74:77], v[58:61]
	v_mfma_f32_16x16x32_bf16 v[38:41], v[84:87], v[78:81], v[38:41]
	ds_read2_b64 v[84:87], v90 offset0:232 offset1:236
	s_waitcnt lgkmcnt(0)
	v_mov_b32_e32 v88, v84
	v_mov_b32_e32 v89, v85
	s_nop 1
	v_mfma_f32_16x16x32_bf16 v[54:57], v[86:89], v[74:77], v[54:57]
	ds_read2_b64 v[74:77], v91 offset0:136 offset1:140
	s_waitcnt lgkmcnt(0)
	v_mfma_f32_16x16x32_bf16 v[62:65], v[74:77], v[66:69], v[62:65]
	v_mfma_f32_16x16x32_bf16 v[46:49], v[74:77], v[70:73], v[46:49]
	ds_read2_b64 v[74:77], v92 offset0:168 offset1:172
	v_mfma_f32_16x16x32_bf16 v[34:37], v[86:89], v[78:81], v[34:37]
	s_waitcnt lgkmcnt(0)
	v_mov_b32_e32 v78, v74
	v_mov_b32_e32 v79, v75
	s_nop 1
	v_mfma_f32_16x16x32_bf16 v[50:53], v[76:79], v[66:69], v[50:53]
	v_mfma_f32_16x16x32_bf16 v[42:45], v[76:79], v[70:73], v[42:45]
	ds_read2_b64 v[74:77], v93 offset0:192 offset1:196
	s_waitcnt lgkmcnt(0)
	v_mfma_f32_16x16x32_bf16 v[58:61], v[74:77], v[66:69], v[58:61]
	v_mfma_f32_16x16x32_bf16 v[38:41], v[74:77], v[70:73], v[38:41]
	ds_read2_b64 v[74:77], v90 offset0:224 offset1:228
	s_waitcnt lgkmcnt(0)
	v_mov_b32_e32 v78, v74
	v_mov_b32_e32 v79, v75
	s_nop 1
	v_mfma_f32_16x16x32_bf16 v[54:57], v[76:79], v[66:69], v[54:57]
	v_mfma_f32_16x16x32_bf16 v[34:37], v[76:79], v[70:73], v[34:37]
	s_branch .LBB0_760

.LBB0_776:
	s_setprio 0
	v_cmp_le_i32_e32 vcc, s35, v101
	s_xor_b64 s[6:7], s[38:39], -1
	s_and_b64 s[10:11], vcc, s[6:7]
	s_and_saveexec_b64 s[6:7], s[10:11]
	s_cbranch_execz .LBB0_778
	s_mul_i32 s10, s26, 0x4800
	v_add_u32_e32 v169, s10, v154
	v_add_u32_e32 v0, v169, v153
	ds_read_b128 v[66:69], v0
	ds_read_b128 v[74:77], v0 offset:64
	ds_read_b128 v[78:81], v0 offset:2304
	ds_read_b128 v[82:85], v0 offset:2368
	ds_read_b128 v[90:93], v0 offset:4608
	ds_read_b128 v[108:111], v0 offset:4672
	ds_read_b128 v[116:119], v0 offset:6912
	ds_read_b128 v[120:123], v0 offset:6976
	s_waitcnt vmcnt(3) lgkmcnt(7)
	s_setprio 3
	v_mfma_f32_16x16x32_bf16 v[70:73], v[66:69], v[2:5], 0
	v_cmp_lt_i32_e32 vcc, v184, v182
	s_mov_b32 s30, 0x3f317218
	v_mov_b32_e32 v214, v1
	s_waitcnt vmcnt(2) lgkmcnt(6)
	v_mfma_f32_16x16x32_bf16 v[130:133], v[74:77], v[6:9], v[70:73]
	v_cndmask_b32_e32 v0, v180, v184, vcc
	v_lshlrev_b32_e32 v204, 2, v0
	v_cmp_lt_i32_e32 vcc, v183, v182
	s_waitcnt lgkmcnt(1)
	v_mfma_f32_16x16x32_bf16 v[126:129], v[116:119], v[2:5], 0
	v_mov_b32_e32 v216, v1
	s_nop 1
	v_mul_f32_e32 v70, 0x3e000000, v130
	v_mul_f32_e64 v71, |v70|, s41
	v_exp_f32_e32 v71, v71
	v_max_f32_e32 v70, 0, v70
	v_cndmask_b32_e32 v72, v180, v183, vcc
	v_mfma_f32_16x16x32_bf16 v[112:115], v[90:93], v[2:5], 0
	v_add_f32_e32 v0, 1.0, v71
	v_log_f32_e32 v0, v0
	v_lshlrev_b32_e32 v203, 2, v72
	s_waitcnt vmcnt(1)
	v_mfma_f32_16x16x32_bf16 v[134:137], v[90:93], v[14:17], 0
	v_cmp_ne_u32_e32 vcc, 0, v168
	v_fmac_f32_e32 v70, 0x3f317218, v0
	v_mul_f32_e32 v0, 0x3e000000, v131
	v_fma_f32 v145, v130, s4, -v70
	v_add_f32_e32 v212, 0, v70
	v_mul_f32_e64 v90, |v0|, s41
	s_waitcnt lgkmcnt(0)
	v_mfma_f32_16x16x32_bf16 v[70:73], v[120:123], v[6:9], v[126:129]
	v_max_f32_e32 v0, 0, v0
	s_or_b64 s[10:11], s[48:49], vcc
	s_or_b64 s[94:95], s[56:57], vcc
	v_mfma_f32_16x16x32_bf16 v[86:89], v[78:81], v[2:5], 0
	v_exp_f32_e32 v126, v90
	s_nop 2
	v_mul_f32_e32 v127, 0x3e000000, v70
	s_or_b64 s[16:17], s[64:65], vcc
	v_mfma_f32_16x16x32_bf16 v[78:81], v[78:81], v[14:17], 0
	v_add_f32_e32 v126, 1.0, v126
	s_or_b64 s[14:15], s[54:55], vcc
	s_or_b64 s[18:19], s[68:69], vcc
	v_mfma_f32_16x16x32_bf16 v[90:93], v[82:85], v[6:9], v[86:89]
	s_or_b64 s[96:97], s[58:59], vcc
	v_cndmask_b32_e64 v226, v193, v145, s[94:95]
	s_or_b64 s[98:99], s[62:63], vcc
	v_mul_f32_e64 v86, |v127|, s41
	v_exp_f32_e32 v128, v86
	v_mfma_f32_16x16x32_bf16 v[86:89], v[108:111], v[6:9], v[112:115]
	v_mov_b32_e32 v145, v1
	s_or_b64 s[20:21], s[80:81], vcc
	s_or_b64 s[22:23], s[84:85], vcc
	v_log_f32_e32 v112, v126
	s_waitcnt vmcnt(0)
	v_mfma_f32_16x16x32_bf16 v[82:85], v[82:85], v[18:21], v[78:81]
	v_add_f32_e32 v113, 1.0, v128
	v_log_f32_e32 v113, v113
	v_fmac_f32_e32 v0, 0x3f317218, v112
	v_mfma_f32_16x16x32_bf16 v[78:81], v[108:111], v[18:21], v[134:137]
	v_mul_f32_e32 v109, 0x3e000000, v132
	v_mul_f32_e64 v110, |v109|, s41
	v_exp_f32_e32 v110, v110
	v_cndmask_b32_e64 v108, 0, v0, s[10:11]
	v_fma_f32 v0, v131, s4, -v0
	v_mul_f32_e32 v111, 0x3e000000, v133
	v_cndmask_b32_e64 v205, v193, v0, s[10:11]
	v_max_f32_e32 v0, 0, v109
	v_add_f32_e32 v109, 1.0, v110
	v_mul_f32_e64 v110, |v111|, s41
	v_log_f32_e32 v109, v109
	v_exp_f32_e32 v112, v110
	s_or_b64 s[10:11], s[50:51], vcc
	v_max_f32_e32 v114, 0, v127
	v_fmac_f32_e32 v0, 0x3f317218, v109
	v_add_f32_e32 v109, 1.0, v112
	v_log_f32_e32 v109, v109
	v_cndmask_b32_e64 v110, 0, v0, s[10:11]
	v_fma_f32 v0, v132, s4, -v0
	v_cndmask_b32_e64 v206, v193, v0, s[10:11]
	v_max_f32_e32 v0, 0, v111
	v_fmac_f32_e32 v0, 0x3f317218, v109
	v_mul_f32_e32 v109, 0x3e000000, v90
	v_mul_f32_e64 v111, |v109|, s41
	v_exp_f32_e32 v111, v111
	s_or_b64 s[10:11], s[52:53], vcc
	v_cndmask_b32_e64 v112, 0, v0, s[10:11]
	v_fma_f32 v0, v133, s4, -v0
	v_cndmask_b32_e64 v207, v193, v0, s[10:11]
	v_add_f32_e32 v0, 1.0, v111
	v_mul_f32_e32 v111, 0x3e000000, v91
	v_mfma_f32_16x16x32_bf16 v[66:69], v[66:69], v[14:17], 0
	v_fmac_f32_e32 v114, 0x3f317218, v113
	v_mul_f32_e64 v113, |v111|, s41
	v_log_f32_e32 v0, v0
	v_mfma_f32_16x16x32_bf16 v[116:119], v[116:119], v[14:17], 0
	v_exp_f32_e32 v113, v113
	s_or_b64 s[10:11], s[60:61], vcc
	v_cndmask_b32_e64 v132, 0, v212, s[94:95]
	v_mfma_f32_16x16x32_bf16 v[66:69], v[74:77], v[18:21], v[66:69]
	v_mov_b32_e32 v212, v1
	s_or_b64 s[12:13], s[86:87], vcc
	s_or_b64 s[24:25], s[88:89], vcc
	v_mfma_f32_16x16x32_bf16 v[74:77], v[120:123], v[18:21], v[116:119]
	s_setprio 0
	v_fma_f32 v70, v70, s4, -v114
	v_cndmask_b32_e32 v70, v193, v70, vcc
	s_nop 0
	v_max_f32_e32 v118, 0, v109
	v_fmac_f32_e32 v118, 0x3f317218, v0
	v_add_f32_e32 v0, 1.0, v113
	v_mul_f32_e32 v113, 0x3e000000, v92
	v_log_f32_e32 v109, v0
	v_mul_f32_e64 v0, |v113|, s41
	v_exp_f32_e32 v115, v0
	v_max_f32_e32 v0, 0, v111
	v_mul_f32_e32 v148, 0x3f317218, v109
	v_max_f32_e32 v150, 0, v113
	v_add_f32_e32 v109, 1.0, v115
	v_log_f32_e32 v196, v109
	v_mul_f32_e32 v109, 0x3e000000, v93
	v_mul_f32_e64 v111, |v109|, s41
	v_mul_f32_e32 v113, 0x3e000000, v86
	v_exp_f32_e32 v111, v111
	v_mul_f32_e64 v115, |v113|, s41
	v_exp_f32_e32 v115, v115
	v_max_f32_e32 v198, 0, v109
	v_add_f32_e32 v109, 1.0, v111
	v_log_f32_e32 v210, v109
	v_add_f32_e32 v109, 1.0, v115
	v_mul_f32_e32 v111, 0x3e000000, v87
	v_log_f32_e32 v109, v109
	v_mul_f32_e64 v115, |v111|, s41
	v_exp_f32_e32 v115, v115
	v_max_f32_e32 v134, 0, v113
	v_fmac_f32_e32 v134, 0x3f317218, v109
	v_mul_f32_e32 v109, 0x3e000000, v88
	v_fma_f32 v113, v86, s4, -v134
	v_add_f32_e32 v86, 1.0, v115
	v_mul_f32_e64 v115, |v109|, s41
	v_log_f32_e32 v86, v86
	v_exp_f32_e32 v115, v115
	v_max_f32_e32 v144, 0, v111
	v_max_f32_e32 v138, 0, v109
	v_mul_f32_e32 v146, 0x3f317218, v86
	v_add_f32_e32 v86, 1.0, v115
	v_log_f32_e32 v142, v86
	v_mul_f32_e32 v86, 0x3e000000, v89
	v_mul_f32_e64 v109, |v86|, s41
	v_mul_f32_e32 v111, 0x3e000000, v71
	v_exp_f32_e32 v109, v109
	v_mul_f32_e64 v115, |v111|, s41
	v_exp_f32_e32 v115, v115
	v_max_f32_e32 v136, 0, v86
	v_add_f32_e32 v86, 1.0, v109
	v_log_f32_e32 v140, v86
	v_add_f32_e32 v86, 1.0, v115
	v_mul_f32_e32 v115, 0x3e000000, v72
	v_log_f32_e32 v109, v86
	v_mul_f32_e64 v86, |v115|, s41
	v_exp_f32_e32 v116, v86
	v_max_f32_e32 v86, 0, v111
	v_mul_f32_e32 v111, 0x3e000000, v66
	v_max_f32_e32 v120, 0, v115
	v_mul_f32_e64 v115, |v111|, s41
	v_exp_f32_e32 v115, v115
	v_mul_f32_e32 v126, 0x3f317218, v109
	v_add_f32_e32 v109, 1.0, v116
	v_log_f32_e32 v122, v109
	v_mul_f32_e32 v109, 0x3e000000, v73
	v_mul_f32_e64 v116, |v109|, s41
	v_max_f32_e32 v128, 0, v109
	v_add_f32_e32 v109, 1.0, v115
	v_exp_f32_e32 v116, v116
	v_log_f32_e32 v109, v109
	v_max_f32_e32 v111, 0, v111
	v_fma_f32 v90, v90, s4, -v118
	v_add_f32_e32 v115, 1.0, v116
	v_fmac_f32_e32 v111, 0x3f317218, v109
	v_mul_f32_e32 v109, 0x3e000000, v67
	v_log_f32_e32 v130, v115
	v_mul_f32_e64 v115, |v109|, s41
	v_exp_f32_e32 v115, v115
	v_fma_f32 v208, v66, s4, -v111
	v_add_f32_e32 v133, 0, v111
	v_mul_f32_e32 v111, 0x3e000000, v68
	v_add_f32_e32 v66, 1.0, v115
	v_log_f32_e32 v66, v66
	v_mul_f32_e64 v115, |v111|, s41
	v_exp_f32_e32 v115, v115
	v_max_f32_e32 v109, 0, v109
	v_fmac_f32_e32 v109, 0x3f317218, v66
	v_fma_f32 v209, v67, s4, -v109
	v_add_f32_e32 v67, 1.0, v115
	v_log_f32_e32 v116, v67
	v_mul_f32_e32 v67, 0x3e000000, v69
	v_max_f32_e32 v66, 0, v111
	v_mul_f32_e64 v111, |v67|, s41
	v_mul_f32_e32 v115, 0x3e000000, v82
	v_exp_f32_e32 v111, v111
	v_mul_f32_e64 v117, |v115|, s41
	v_exp_f32_e32 v119, v117
	v_max_f32_e32 v149, 0, v115
	v_add_f32_e32 v111, 1.0, v111
	v_log_f32_e32 v117, v111
	v_add_f32_e32 v111, 1.0, v119
	v_mul_f32_e32 v119, 0x3e000000, v83
	v_mul_f32_e64 v121, |v119|, s41
	v_log_f32_e32 v111, v111
	v_exp_f32_e32 v121, v121
	v_mul_f32_e32 v115, 0x3e000000, v84
	v_max_f32_e32 v213, 0, v119
	v_fmac_f32_e32 v149, 0x3f317218, v111
	v_add_f32_e32 v111, 1.0, v121
	v_mul_f32_e64 v121, |v115|, s41
	v_log_f32_e32 v111, v111
	v_exp_f32_e32 v121, v121
	v_max_f32_e32 v151, 0, v115
	v_fma_f32 v82, v82, s4, -v149
	v_mul_f32_e32 v119, 0x3f317218, v111
	v_add_f32_e32 v111, 1.0, v121
	v_log_f32_e32 v197, v111
	v_mul_f32_e32 v111, 0x3e000000, v85
	v_mul_f32_e64 v115, |v111|, s41
	v_mul_f32_e32 v121, 0x3e000000, v78
	v_exp_f32_e32 v115, v115
	v_mul_f32_e64 v123, |v121|, s41
	v_exp_f32_e32 v123, v123
	v_max_f32_e32 v199, 0, v111
	v_add_f32_e32 v111, 1.0, v115
	v_mul_f32_e32 v115, 0x3e000000, v79
	v_log_f32_e32 v211, v111
	v_add_f32_e32 v111, 1.0, v123
	v_mul_f32_e64 v123, |v115|, s41
	v_log_f32_e32 v111, v111
	v_exp_f32_e32 v123, v123
	v_max_f32_e32 v147, 0, v121
	v_mul_f32_e32 v121, 0x3e000000, v80
	v_fmac_f32_e32 v147, 0x3f317218, v111
	v_add_f32_e32 v111, 1.0, v123
	v_mul_f32_e64 v123, |v121|, s41
	v_log_f32_e32 v111, v111
	v_exp_f32_e32 v123, v123
	v_max_f32_e32 v215, 0, v115
	v_max_f32_e32 v139, 0, v121
	v_mul_f32_e32 v135, 0x3f317218, v111
	v_add_f32_e32 v111, 1.0, v123
	v_log_f32_e32 v143, v111
	v_mul_f32_e32 v111, 0x3e000000, v81
	v_mul_f32_e64 v115, |v111|, s41
	v_mul_f32_e32 v121, 0x3e000000, v74
	v_exp_f32_e32 v115, v115
	v_mul_f32_e64 v123, |v121|, s41
	v_exp_f32_e32 v123, v123
	v_max_f32_e32 v137, 0, v111
	v_add_f32_e32 v111, 1.0, v115
	v_mul_f32_e32 v115, 0x3e000000, v75
	v_log_f32_e32 v141, v111
	v_add_f32_e32 v111, 1.0, v123
	v_mul_f32_e64 v123, |v115|, s41
	v_log_f32_e32 v111, v111
	v_exp_f32_e32 v123, v123
	v_max_f32_e32 v127, 0, v121
	v_max_f32_e32 v217, 0, v115
	v_fmac_f32_e32 v127, 0x3f317218, v111
	v_add_f32_e32 v111, 1.0, v123
	v_log_f32_e32 v111, v111
	v_pk_add_f32 v[218:219], v[0:1], v[148:149]
	v_pk_fma_f32 v[148:149], v[196:197], s[30:31], v[150:151] op_sel_hi:[1,0,1]
	v_pk_fma_f32 v[150:151], v[210:211], s[30:31], v[198:199] op_sel_hi:[1,0,1]
	v_mul_f32_e32 v115, 0x3f317218, v111
	v_mul_f32_e32 v111, 0x3e000000, v76
	v_mul_f32_e64 v121, |v111|, s41
	v_exp_f32_e32 v123, v121
	v_max_f32_e32 v121, 0, v111
	v_mul_f32_e32 v111, 0x3e000000, v77
	v_mul_f32_e64 v129, |v111|, s41
	v_exp_f32_e32 v131, v129
	v_max_f32_e32 v129, 0, v111
	v_pk_add_f32 v[198:199], v[212:213], v[118:119]
	v_fma_f32 v0, v91, s4, -v218
	v_add_f32_e32 v111, 1.0, v131
	v_log_f32_e32 v131, v111
	v_cndmask_b32_e64 v111, v193, v90, s[10:11]
	v_fma_f32 v90, v92, s4, -v148
	v_cndmask_b32_e64 v227, v193, v90, s[16:17]
	v_fma_f32 v90, v93, s4, -v150
	v_cndmask_b32_e64 v228, v193, v90, s[18:19]
	v_cndmask_b32_e64 v197, 0, v219, s[94:95]
	v_cndmask_b32_e64 v196, 0, v218, s[14:15]
	v_cndmask_b32_e64 v91, 0, v199, s[96:97]
	v_cndmask_b32_e64 v90, 0, v198, s[10:11]
	v_pk_add_f32 v[118:119], v[196:197], v[90:91]
	v_cndmask_b32_e64 v93, 0, v149, s[98:99]
	v_cndmask_b32_e64 v92, 0, v148, s[16:17]
	v_pk_add_f32 v[144:145], v[144:145], v[146:147]
	v_pk_add_f32 v[210:211], v[92:93], v[118:119]
	v_cndmask_b32_e64 v118, 0, v150, s[18:19]
	s_or_b64 s[18:19], s[76:77], vcc
	v_fma_f32 v87, v87, s4, -v144
	s_or_b64 s[16:17], s[72:73], vcc
	v_fma_f32 v78, v78, s4, -v147
	v_cndmask_b32_e64 v0, v193, v0, s[14:15]
	v_cndmask_b32_e64 v90, v193, v113, s[18:19]
	v_cndmask_b32_e64 v113, v193, v87, s[16:17]
	v_pk_fma_f32 v[142:143], v[142:143], s[30:31], v[138:139] op_sel_hi:[1,0,1]
	s_or_b64 s[14:15], s[70:71], vcc
	v_cndmask_b32_e64 v144, 0, v144, s[16:17]
	v_pk_add_f32 v[146:147], v[214:215], v[134:135]
	s_or_b64 s[16:17], s[74:75], vcc
	s_or_b64 s[10:11], s[66:67], vcc
	v_fma_f32 v87, v88, s4, -v142
	v_pk_fma_f32 v[140:141], v[140:141], s[30:31], v[136:137] op_sel_hi:[1,0,1]
	v_cndmask_b32_e64 v145, 0, v145, s[14:15]
	v_cndmask_b32_e64 v135, 0, v147, s[16:17]
	v_cndmask_b32_e64 v134, 0, v146, s[18:19]
	s_or_b64 s[18:19], s[78:79], vcc
	v_cndmask_b32_e64 v119, 0, v151, s[10:11]
	v_cndmask_b32_e64 v148, v193, v87, s[20:21]
	v_fma_f32 v87, v89, s4, -v140
	v_pk_add_f32 v[88:89], v[144:145], v[134:135]
	v_cndmask_b32_e64 v137, 0, v143, s[18:19]
	v_cndmask_b32_e64 v136, 0, v142, s[20:21]
	s_or_b64 s[20:21], s[82:83], vcc
	v_pk_add_f32 v[210:211], v[118:119], v[210:211]
	v_pk_add_f32 v[88:89], v[136:137], v[88:89]
	v_cndmask_b32_e64 v139, 0, v141, s[20:21]
	v_cndmask_b32_e64 v138, 0, v140, s[22:23]
	ds_bpermute_b32 v212, v204, v210
	ds_bpermute_b32 v213, v204, v211
	v_pk_add_f32 v[88:89], v[138:139], v[88:89]
	ds_bpermute_b32 v214, v204, v88
	ds_bpermute_b32 v215, v204, v89
	v_add_f32_e32 v123, 1.0, v123
	s_waitcnt lgkmcnt(2)
	v_pk_add_f32 v[210:211], v[210:211], v[212:213]
	ds_bpermute_b32 v218, v203, v210
	v_log_f32_e32 v123, v123
	s_waitcnt lgkmcnt(1)
	v_pk_add_f32 v[220:221], v[88:89], v[214:215]
	ds_bpermute_b32 v222, v203, v220
	v_cndmask_b32_e64 v150, v193, v87, s[22:23]
	v_cndmask_b32_e64 v87, 0, v212, s[44:45]
	s_waitcnt lgkmcnt(1)
	v_cndmask_b32_e64 v88, 0, v218, s[46:47]
	v_add_f32_e32 v134, v87, v88
	v_cndmask_b32_e64 v87, 0, v214, s[44:45]
	s_waitcnt lgkmcnt(0)
	v_cndmask_b32_e64 v88, 0, v222, s[46:47]
	v_add_f32_e32 v140, v87, v88
	v_mov_b32_e32 v87, v1
	v_fma_f32 v74, v74, s4, -v127
	v_pk_add_f32 v[86:87], v[86:87], v[126:127]
	v_pk_fma_f32 v[126:127], v[130:131], s[30:31], v[128:129] op_sel_hi:[1,0,1]
	v_pk_add_f32 v[130:131], v[216:217], v[114:115]
	v_cndmask_b32_e64 v74, v193, v74, s[12:13]
	v_pk_fma_f32 v[122:123], v[122:123], s[30:31], v[120:121] op_sel_hi:[1,0,1]
	v_cndmask_b32_e64 v129, 0, v87, s[12:13]
	v_cndmask_b32_e32 v128, 0, v86, vcc
	v_cndmask_b32_e64 v89, 0, v131, s[24:25]
	v_cndmask_b32_e32 v88, 0, v130, vcc
	s_or_b64 s[12:13], s[90:91], vcc
	v_pk_add_f32 v[120:121], v[128:129], v[88:89]
	v_cndmask_b32_e64 v115, 0, v123, s[12:13]
	v_cndmask_b32_e32 v114, 0, v122, vcc
	s_or_b64 s[22:23], s[92:93], vcc
	v_pk_add_f32 v[216:217], v[114:115], v[120:121]
	v_cndmask_b32_e64 v121, 0, v127, s[22:23]
	v_cndmask_b32_e32 v120, 0, v126, vcc
	v_pk_add_f32 v[216:217], v[120:121], v[216:217]
	ds_bpermute_b32 v224, v204, v216
	ds_bpermute_b32 v225, v204, v217
	v_fma_f32 v71, v71, s4, -v86
	ds_bpermute_b32 v219, v203, v211
	ds_bpermute_b32 v223, v203, v221
	v_fma_f32 v72, v72, s4, -v122
	s_waitcnt lgkmcnt(2)
	v_pk_add_f32 v[86:87], v[216:217], v[224:225]
	ds_bpermute_b32 v216, v203, v86
	ds_bpermute_b32 v217, v203, v87
	v_cndmask_b32_e32 v88, v193, v72, vcc
	v_fma_f32 v72, v73, s4, -v126
	v_cndmask_b32_e32 v122, v193, v72, vcc
	v_cndmask_b32_e64 v72, 0, v224, s[44:45]
	s_waitcnt lgkmcnt(1)
	v_cndmask_b32_e64 v73, 0, v216, s[46:47]
	s_waitcnt lgkmcnt(0)
	v_pk_add_f32 v[86:87], v[86:87], v[216:217]
	v_add_f32_e32 v126, v72, v73
	v_pk_add_f32 v[72:73], v[210:211], v[218:219]
	v_pk_add_f32 v[210:211], v[220:221], v[222:223]
	v_pk_add_f32 v[220:221], v[106:107], v[86:87]
	v_add_f32_e32 v106, v106, v126
	v_pk_add_f32 v[210:211], v[210:211], v[220:221]
	v_add_f32_e32 v120, v120, v106
	v_pk_add_f32 v[86:87], v[72:73], v[210:211]
	v_add_f32_e32 v72, v134, v210
	v_add_f32_e32 v73, v118, v72
	v_add_f32_e32 v92, v92, v73
	v_add_f32_e32 v118, v196, v92
	v_sub_f32_e32 v0, v0, v92
	v_sub_f32_e32 v92, v111, v118
	v_add_f32_e32 v111, v140, v220
	v_add_f32_e32 v118, v138, v111
	v_sub_f32_e32 v72, v228, v72
	v_sub_f32_e32 v73, v227, v73
	v_add_f32_e32 v129, v136, v118
	v_sub_f32_e32 v106, v122, v106
	v_sub_f32_e32 v88, v88, v120
	v_mul_f32_e32 v72, 0x3fb8aa3b, v72
	v_mul_f32_e32 v73, 0x3fb8aa3b, v73
	v_mul_f32_e32 v0, 0x3fb8aa3b, v0
	v_mul_f32_e32 v92, 0x3fb8aa3b, v92
	v_add_f32_e32 v130, v144, v129
	v_mul_f32_e32 v106, 0x3fb8aa3b, v106
	v_mul_f32_e32 v88, 0x3fb8aa3b, v88
	v_exp_f32_e32 v72, v72
	v_exp_f32_e32 v73, v73
	v_exp_f32_e32 v0, v0
	v_exp_f32_e32 v92, v92
	v_sub_f32_e32 v113, v113, v129
	v_sub_f32_e32 v90, v90, v130
	v_exp_f32_e32 v106, v106
	v_exp_f32_e32 v88, v88
	v_mul_f32_e32 v113, 0x3fb8aa3b, v113
	v_mul_f32_e32 v90, 0x3fb8aa3b, v90
	v_add_f32_e32 v114, v114, v120
	v_cndmask_b32_e32 v71, v193, v71, vcc
	v_sub_f32_e32 v111, v150, v111
	v_sub_f32_e32 v118, v148, v118
	v_exp_f32_e32 v113, v113
	v_exp_f32_e32 v90, v90
	v_add_f32_e32 v126, v128, v114
	v_mul_f32_e32 v111, 0x3fb8aa3b, v111
	v_mul_f32_e32 v118, 0x3fb8aa3b, v118
	v_sub_f32_e32 v71, v71, v114
	v_sub_f32_e32 v70, v70, v126
	v_exp_f32_e32 v111, v111
	v_exp_f32_e32 v118, v118
	v_mul_f32_e32 v71, 0x3fb8aa3b, v71
	v_mul_f32_e32 v70, 0x3fb8aa3b, v70
	v_cvt_pk_bf16_f32 v128, v92, v0
	v_cvt_pk_bf16_f32 v129, v73, v72
	v_cvt_pk_bf16_f32 v73, v88, v106
	v_cndmask_b32_e64 v0, v193, v82, s[94:95]
	v_fma_f32 v82, v83, s4, -v199
	v_fma_f32 v83, v84, s4, -v149
	v_fma_f32 v84, v85, s4, -v151
	v_cndmask_b32_e64 v85, 0, v213, s[44:45]
	v_cndmask_b32_e64 v88, 0, v219, s[46:47]
	v_exp_f32_e32 v114, v71
	v_exp_f32_e32 v120, v70
	v_add_f32_e32 v85, v85, v88
	v_cndmask_b32_e64 v88, v193, v78, s[14:15]
	v_fma_f32 v78, v79, s4, -v147
	v_max_f32_e32 v67, 0, v67
	v_cvt_pk_bf16_f32 v70, v90, v113
	v_cndmask_b32_e64 v90, v193, v78, s[16:17]
	v_fma_f32 v78, v80, s4, -v143
	v_cndmask_b32_e64 v92, v193, v78, s[18:19]
	v_fma_f32 v78, v81, s4, -v141
	v_pk_fma_f32 v[66:67], v[116:117], s[30:31], v[66:67] op_sel_hi:[1,0,1]
	v_pk_add_f32 v[132:133], v[108:109], v[132:133]
	v_cvt_pk_bf16_f32 v71, v118, v111
	v_cndmask_b32_e64 v106, v193, v78, s[20:21]
	v_cndmask_b32_e64 v78, 0, v215, s[44:45]
	v_cndmask_b32_e64 v79, 0, v223, s[46:47]
	v_mov_b32_e32 v111, v66
	v_cvt_pk_bf16_f32 v72, v120, v114
	v_add_f32_e32 v114, v78, v79
	v_pk_add_f32 v[78:79], v[110:111], v[132:133]
	v_mov_b32_e32 v113, v67
	v_pk_add_f32 v[78:79], v[112:113], v[78:79]
	ds_bpermute_b32 v80, v204, v78
	ds_bpermute_b32 v81, v204, v79
	v_fma_f32 v76, v76, s4, -v123
	v_cndmask_b32_e64 v111, v193, v76, s[12:13]
	v_fma_f32 v76, v77, s4, -v127
	v_cndmask_b32_e64 v113, v193, v76, s[22:23]
	s_waitcnt lgkmcnt(0)
	v_pk_add_f32 v[116:117], v[78:79], v[80:81]
	ds_bpermute_b32 v122, v203, v116
	v_cndmask_b32_e64 v76, 0, v225, s[44:45]
	v_cndmask_b32_e64 v77, 0, v217, s[46:47]
	v_add_f32_e32 v76, v76, v77
	v_cndmask_b32_e64 v77, 0, v80, s[44:45]
	s_waitcnt lgkmcnt(0)
	v_cndmask_b32_e64 v78, 0, v122, s[46:47]
	v_add_f32_e32 v77, v77, v78
	v_add_f32_e32 v77, v77, v86
	v_add_f32_e32 v78, v112, v77
	v_add_f32_e32 v79, v110, v78
	v_sub_f32_e32 v77, v207, v77
	v_sub_f32_e32 v78, v206, v78
	v_mul_f32_e32 v77, 0x3fb8aa3b, v77
	v_mul_f32_e32 v78, 0x3fb8aa3b, v78
	ds_bpermute_b32 v123, v203, v117
	v_exp_f32_e32 v77, v77
	v_exp_f32_e32 v78, v78
	v_add_f32_e32 v80, v108, v79
	v_sub_f32_e32 v79, v205, v79
	v_sub_f32_e32 v80, v226, v80
	v_cvt_pk_bf16_f32 v127, v78, v77
	v_cndmask_b32_e64 v77, 0, v81, s[44:45]
	s_waitcnt lgkmcnt(0)
	v_cndmask_b32_e64 v78, 0, v123, s[46:47]
	v_add_f32_e32 v77, v77, v78
	v_add_f32_e32 v77, v77, v87
	v_mul_f32_e32 v79, 0x3fb8aa3b, v79
	v_mul_f32_e32 v80, 0x3fb8aa3b, v80
	v_fma_f32 v69, v69, s4, -v67
	v_add_f32_e32 v67, v77, v67
	v_exp_f32_e32 v79, v79
	v_exp_f32_e32 v80, v80
	v_add_f32_e32 v78, v66, v67
	v_fma_f32 v66, v68, s4, -v66
	v_sub_f32_e32 v66, v66, v67
	v_mul_f32_e32 v66, 0x3fb8aa3b, v66
	v_exp_f32_e32 v108, v66
	v_sub_f32_e32 v66, v209, v78
	v_cvt_pk_bf16_f32 v126, v80, v79
	v_add_f32_e32 v79, v109, v78
	v_mul_f32_e32 v66, 0x3fb8aa3b, v66
	v_exp_f32_e32 v78, v66
	v_sub_f32_e32 v66, v208, v79
	v_mul_f32_e32 v66, 0x3fb8aa3b, v66
	v_cndmask_b32_e64 v84, v193, v84, s[10:11]
	v_exp_f32_e32 v79, v66
	v_add_f32_e32 v66, v85, v211
	v_add_f32_e32 v67, v119, v66
	v_sub_f32_e32 v66, v84, v66
	v_cndmask_b32_e64 v83, v193, v83, s[98:99]
	v_mul_f32_e32 v66, 0x3fb8aa3b, v66
	v_exp_f32_e32 v84, v66
	v_sub_f32_e32 v66, v83, v67
	v_cndmask_b32_e64 v82, v193, v82, s[96:97]
	v_add_f32_e32 v68, v93, v67
	v_mul_f32_e32 v66, 0x3fb8aa3b, v66
	v_sub_f32_e32 v69, v69, v77
	v_exp_f32_e32 v85, v66
	v_sub_f32_e32 v66, v82, v68
	v_mul_f32_e32 v69, 0x3fb8aa3b, v69
	v_mul_f32_e32 v66, 0x3fb8aa3b, v66
	v_exp_f32_e32 v77, v69
	v_add_f32_e32 v69, v91, v68
	v_exp_f32_e32 v91, v66
	v_add_f32_e32 v66, v114, v221
	v_add_f32_e32 v67, v139, v66
	v_sub_f32_e32 v66, v106, v66
	v_mul_f32_e32 v66, 0x3fb8aa3b, v66
	v_exp_f32_e32 v93, v66
	v_sub_f32_e32 v66, v92, v67
	v_add_f32_e32 v68, v137, v67
	v_mul_f32_e32 v66, 0x3fb8aa3b, v66
	v_exp_f32_e32 v92, v66
	v_sub_f32_e32 v66, v90, v68
	v_sub_f32_e32 v0, v0, v69
	v_add_f32_e32 v69, v135, v68
	v_mul_f32_e32 v66, 0x3fb8aa3b, v66
	v_exp_f32_e32 v90, v66
	v_sub_f32_e32 v66, v88, v69
	v_lshl_add_u32 v88, v155, 1, v169
	v_add_u32_e32 v106, 0x2000, v88
	v_mul_f32_e32 v80, 0x3fb8aa3b, v66
	ds_read2_b64 v[66:69], v106 offset0:128 offset1:132
	v_add_u32_e32 v110, 0x2800, v88
	v_exp_f32_e32 v109, v80
	ds_read2_b64 v[80:83], v110 offset0:160 offset1:164
	v_mul_f32_e32 v0, 0x3fb8aa3b, v0
	v_exp_f32_e32 v0, v0
	v_add_f32_e32 v107, v107, v76
	v_cvt_pk_bf16_f32 v76, v79, v78
	v_cvt_pk_bf16_f32 v79, v85, v84
	s_waitcnt lgkmcnt(0)
	v_mov_b32_e32 v84, v80
	v_mov_b32_e32 v85, v81
	v_cvt_pk_bf16_f32 v77, v108, v77
	v_cvt_pk_bf16_f32 v78, v0, v91
	v_add_u32_e32 v108, 0x3000, v88
	s_setprio 3
	v_mfma_f32_16x16x32_bf16 v[62:65], v[66:69], v[126:129], v[62:65]
	v_sub_f32_e32 v80, v113, v107
	v_add_u32_e32 v88, 0x3800, v88
	v_add_f32_e32 v0, v121, v107
	v_mfma_f32_16x16x32_bf16 v[54:57], v[66:69], v[76:79], v[54:57]
	ds_read2_b64 v[66:69], v108 offset0:200 offset1:204
	v_mul_f32_e32 v107, 0x3fb8aa3b, v80
	v_fma_f32 v75, v75, s4, -v131
	v_mfma_f32_16x16x32_bf16 v[58:61], v[82:85], v[126:129], v[58:61]
	v_add_f32_e32 v91, v115, v0
	v_cndmask_b32_e64 v75, v193, v75, s[24:25]
	v_add_f32_e32 v89, v89, v91
	v_mfma_f32_16x16x32_bf16 v[46:49], v[82:85], v[76:79], v[46:49]
	ds_read2_b64 v[80:83], v88 offset0:232 offset1:236
	v_sub_f32_e32 v0, v111, v0
	v_sub_f32_e32 v75, v75, v91
	s_waitcnt lgkmcnt(1)
	v_mfma_f32_16x16x32_bf16 v[50:53], v[66:69], v[126:129], v[50:53]
	v_sub_f32_e32 v74, v74, v89
	s_waitcnt lgkmcnt(0)
	v_mov_b32_e32 v84, v80
	v_mov_b32_e32 v85, v81
	v_mfma_f32_16x16x32_bf16 v[42:45], v[66:69], v[76:79], v[42:45]
	ds_read2_b64 v[66:69], v106 offset0:136 offset1:140
	v_mul_f32_e32 v0, 0x3fb8aa3b, v0
	v_mul_f32_e32 v75, 0x3fb8aa3b, v75
	v_mul_f32_e32 v74, 0x3fb8aa3b, v74
	v_exp_f32_e32 v107, v107
	v_exp_f32_e32 v0, v0
	v_exp_f32_e32 v91, v75
	v_mfma_f32_16x16x32_bf16 v[34:37], v[82:85], v[76:79], v[34:37]
	v_exp_f32_e32 v76, v74
	ds_read2_b64 v[78:81], v110 offset0:168 offset1:172
	v_cvt_pk_bf16_f32 v74, v109, v90
	v_cvt_pk_bf16_f32 v75, v92, v93
	v_cvt_pk_bf16_f32 v76, v76, v91
	v_cvt_pk_bf16_f32 v77, v0, v107
	s_waitcnt lgkmcnt(1)
	v_mfma_f32_16x16x32_bf16 v[62:65], v[66:69], v[70:73], v[62:65]
	s_mov_b32 s10, 0x42b40000
	s_mov_b32 s97, 0x27c0000
	s_mov_b32 s96, 0x800000
	v_mfma_f32_16x16x32_bf16 v[54:57], v[66:69], v[74:77], v[54:57]
	s_waitcnt lgkmcnt(0)
	v_mov_b32_e32 v66, v80
	v_mov_b32_e32 v67, v81
	v_mov_b32_e32 v68, v78
	v_mov_b32_e32 v69, v79
	ds_read2_b64 v[78:81], v88 offset0:224 offset1:228
	v_mfma_f32_16x16x32_bf16 v[38:41], v[82:85], v[126:129], v[38:41]
	s_mov_b32 s30, 0x27e0000
	v_mfma_f32_16x16x32_bf16 v[58:61], v[66:69], v[70:73], v[58:61]
	v_mfma_f32_16x16x32_bf16 v[46:49], v[66:69], v[74:77], v[46:49]
	ds_read2_b64 v[66:69], v108 offset0:192 offset1:196
	s_waitcnt lgkmcnt(0)
	v_mfma_f32_16x16x32_bf16 v[50:53], v[66:69], v[70:73], v[50:53]
	v_mfma_f32_16x16x32_bf16 v[42:45], v[66:69], v[74:77], v[42:45]
	v_mov_b32_e32 v66, v80
	v_mov_b32_e32 v67, v81
	v_mov_b32_e32 v68, v78
	v_mov_b32_e32 v69, v79
	s_nop 1
	v_mfma_f32_16x16x32_bf16 v[38:41], v[66:69], v[70:73], v[38:41]
	v_add_f32_e64 v70, v116, v122
	v_add_f32_e64 v71, v117, v123
	v_pk_add_f32 v[106:107], v[70:71], v[86:87]
	v_mfma_f32_16x16x32_bf16 v[34:37], v[66:69], v[74:77], v[34:37]
	v_cmp_lt_f32_e32 vcc, s10, v106
	v_cmp_lt_f32_e64 s[10:11], s10, v107
	s_and_b64 s[10:11], vcc, s[10:11]
	s_nop 0
	v_cndmask_b32_e64 v0, 0, 1, s[10:11]
	v_cmp_ne_u32_e32 vcc, 0, v0
	s_cmp_eq_u64 vcc, exec
	s_cselect_b64 s[10:11], -1, 0
	s_andn2_b64 s[12:13], s[38:39], exec
	s_and_b64 s[10:11], s[10:11], exec
	s_or_b64 s[38:39], s[12:13], s[10:11]
